# plus nontemporal stores of the down-projection residual output (next reader is far away)
# baseline (speedup 1.0000x reference)
;     __device__ __forceinline__ void operator()(const f32x4 (&acc)[2][2][4][2], const Unit& u, int wr, int wc, int fr, int fq) const {
;         const int row0 = u.pm * BM + wr * 64 + fr, col0 = u.pn * BM + wc * 32 + 4 * fq; const int b = (u.pm * BM) >> 12;
;         f32x4 gv[2][2];
; #pragma unroll
;         for (int bj = 0; bj < 2; ++bj)
; #pragma unroll
;             for (int n = 0; n < 2; ++n) gv[bj][n] = *(const f32x4*)(gate + b * MODW + col0 + bj * HALF + n * 16);
; #pragma unroll
;         for (int ai = 0; ai < 2; ++ai)
; #pragma unroll
;             for (int m = 0; m < 4; ++m) { const size_t off = (size_t)(row0 + ai * HALF + m * 16) * DM + col0;
; #pragma unroll
;                 for (int bj = 0; bj < 2; ++bj)
; #pragma unroll
;                     for (int n = 0; n < 2; ++n) { const f32x4 bs = stream ? __builtin_nontemporal_load((const f32x4*)(xin + off + bj * HALF + n * 16)) : *(const f32x4*)(xin + off + bj * HALF + n * 16);
;                         *(f32x4*)(xout + off + bj * HALF + n * 16) = bs + gv[bj][n] * acc[ai][bj][m][n]; }
;                 if (m & 1) asm volatile("" ::: "memory"); }
.LBB0_1085:
	s_lshr_b32 s22, s44, 4
	s_mulk_i32 s22, 0x3000
	s_ashr_i32 s23, s22, 31
	v_lshl_add_u32 v150, s44, 8, v153
	v_lshl_or_b32 v74, s45, 8, v154
	s_lshl_b64 s[22:23], s[22:23], 2
	v_ashrrev_i32_e32 v151, 31, v150
	s_add_u32 s22, s20, s22
	v_ashrrev_i32_e32 v75, 31, v74
	v_lshlrev_b64 v[146:147], 13, v[150:151]
	s_addc_u32 s23, s21, s23
	v_lshlrev_b64 v[148:149], 2, v[74:75]
	v_lshl_add_u64 v[146:147], s[70:71], 0, v[146:147]
	v_lshl_add_u64 v[74:75], s[22:23], 0, v[148:149]
	v_lshl_add_u64 v[146:147], v[146:147], 0, v[148:149]
	global_load_dwordx4 v[94:97], v[74:75], off
	global_load_dwordx4 v[90:93], v[74:75], off offset:64
	global_load_dwordx4 v[86:89], v[74:75], off offset:512
	s_nop 0
	global_load_dwordx4 v[74:77], v[74:75], off offset:576
	s_mov_b64 s[34:35], 0x100
	s_mov_b64 s[52:53], 0x1d0000
	v_lshl_add_u32 v151, v150, 13, v148
	s_mov_b64 s[22:23], s[70:71]
	global_load_dwordx4 v[218:221], v151, s[22:23]
	global_load_dwordx4 v[222:225], v151, s[22:23] offset:64
	global_load_dwordx4 v[226:229], v151, s[22:23] offset:512
	global_load_dwordx4 v[230:233], v151, s[22:23] offset:576
	s_add_u32 s22, s70, 0x20000
	s_addc_u32 s23, s71, 0
	global_load_dwordx4 v[234:237], v151, s[22:23]
	global_load_dwordx4 v[238:241], v151, s[22:23] offset:64
	global_load_dwordx4 v[242:245], v151, s[22:23] offset:512
	global_load_dwordx4 v[246:249], v151, s[22:23] offset:576
	s_add_u32 s22, s70, 0x40000
	s_addc_u32 s23, s71, 0
	global_load_dwordx4 v[158:161], v151, s[22:23]
	global_load_dwordx4 v[162:165], v151, s[22:23] offset:64
	global_load_dwordx4 v[166:169], v151, s[22:23] offset:512
	global_load_dwordx4 v[170:173], v151, s[22:23] offset:576
	s_add_u32 s22, s70, 0x60000
	s_addc_u32 s23, s71, 0
	global_load_dwordx4 v[174:177], v151, s[22:23]
	global_load_dwordx4 v[182:185], v151, s[22:23] offset:64
	global_load_dwordx4 v[186:189], v151, s[22:23] offset:512
	global_load_dwordx4 v[190:193], v151, s[22:23] offset:576
	s_mov_b64 s[100:101], s[70:71]
	s_waitcnt vmcnt(15)
	v_pk_fma_f32 v[144:145], v[144:145], v[96:97], v[220:221]
	v_pk_fma_f32 v[142:143], v[142:143], v[94:95], v[218:219]
	global_store_dwordx4 v151, v[142:145], s[100:101] nt
	s_add_u32 s22, s70, 0x100000
	s_addc_u32 s23, s71, 0
	global_load_dwordx4 v[218:221], v151, s[22:23]
	s_waitcnt vmcnt(15)
	v_pk_fma_f32 v[140:141], v[140:141], v[92:93], v[224:225]
	v_pk_fma_f32 v[138:139], v[138:139], v[90:91], v[222:223]
	global_store_dwordx4 v151, v[138:141], s[100:101] offset:64 nt
	global_load_dwordx4 v[222:225], v151, s[22:23] offset:64
	s_waitcnt vmcnt(15)
	v_pk_fma_f32 v[136:137], v[136:137], v[88:89], v[228:229]
	v_pk_fma_f32 v[134:135], v[134:135], v[86:87], v[226:227]
	global_store_dwordx4 v151, v[134:137], s[100:101] offset:512 nt
	global_load_dwordx4 v[226:229], v151, s[22:23] offset:512
	s_waitcnt vmcnt(15)
	v_pk_fma_f32 v[132:133], v[132:133], v[76:77], v[232:233]
	v_pk_fma_f32 v[130:131], v[130:131], v[74:75], v[230:231]
	global_store_dwordx4 v151, v[130:133], s[100:101] offset:576 nt
	global_load_dwordx4 v[230:233], v151, s[22:23] offset:576
	s_add_u32 s100, s70, 0x20000
	s_addc_u32 s101, s71, 0
	s_waitcnt vmcnt(15)
	v_pk_fma_f32 v[128:129], v[128:129], v[96:97], v[236:237]
	v_pk_fma_f32 v[126:127], v[126:127], v[94:95], v[234:235]
	global_store_dwordx4 v151, v[126:129], s[100:101] nt
	s_add_u32 s22, s70, 0x120000
	s_addc_u32 s23, s71, 0
	global_load_dwordx4 v[234:237], v151, s[22:23]
	s_waitcnt vmcnt(15)
	v_pk_fma_f32 v[124:125], v[124:125], v[92:93], v[240:241]
	v_pk_fma_f32 v[122:123], v[122:123], v[90:91], v[238:239]
	global_store_dwordx4 v151, v[122:125], s[100:101] offset:64 nt
	global_load_dwordx4 v[238:241], v151, s[22:23] offset:64
	s_waitcnt vmcnt(15)
	v_pk_fma_f32 v[120:121], v[120:121], v[88:89], v[244:245]
	v_pk_fma_f32 v[118:119], v[118:119], v[86:87], v[242:243]
	global_store_dwordx4 v151, v[118:121], s[100:101] offset:512 nt
	global_load_dwordx4 v[242:245], v151, s[22:23] offset:512
	s_waitcnt vmcnt(15)
	v_pk_fma_f32 v[116:117], v[116:117], v[76:77], v[248:249]
	v_pk_fma_f32 v[114:115], v[114:115], v[74:75], v[246:247]
	global_store_dwordx4 v151, v[114:117], s[100:101] offset:576 nt
	global_load_dwordx4 v[246:249], v151, s[22:23] offset:576
	s_add_u32 s100, s70, 0x40000
	s_addc_u32 s101, s71, 0
	s_waitcnt vmcnt(15)
	v_pk_fma_f32 v[112:113], v[112:113], v[96:97], v[160:161]
	v_pk_fma_f32 v[110:111], v[110:111], v[94:95], v[158:159]
	global_store_dwordx4 v151, v[110:113], s[100:101] nt
	s_add_u32 s22, s70, 0x140000
	s_addc_u32 s23, s71, 0
	global_load_dwordx4 v[158:161], v151, s[22:23]
	s_waitcnt vmcnt(15)
	v_pk_fma_f32 v[108:109], v[108:109], v[92:93], v[164:165]
	v_pk_fma_f32 v[106:107], v[106:107], v[90:91], v[162:163]
	global_store_dwordx4 v151, v[106:109], s[100:101] offset:64 nt
	global_load_dwordx4 v[162:165], v151, s[22:23] offset:64
	s_waitcnt vmcnt(15)
; #define PG8_BAR __builtin_amdgcn_s_barrier()
; template <class Epi, class Sched, bool ALIGN_EPI, bool SP2>
; __device__ __forceinline__ void gemm_phase(LAS unsigned char* lds, const int K, const Sched& S, const Epi& E) {
;     ...
;         if constexpr (ALIGN_EPI) { if (wr == 1) PG8_BAR; }
;     }
;     __device__ __forceinline__ void operator()(const f32x4 (&acc)[2][2][4][2], const Unit& u, int wr, int wc, int fr, int fq) const {
;     ...
;             for (int m = 0; m < 4; ++m) { const size_t off = (size_t)(row0 + ai * HALF + m * 16) * DM + col0;
; #pragma unroll
;                 for (int bj = 0; bj < 2; ++bj)
; #pragma unroll
;                     for (int n = 0; n < 2; ++n) { const f32x4 bs = stream ? __builtin_nontemporal_load((const f32x4*)(xin + off + bj * HALF + n * 16)) : *(const f32x4*)(xin + off + bj * HALF + n * 16);
;                         *(f32x4*)(xout + off + bj * HALF + n * 16) = bs + gv[bj][n] * acc[ai][bj][m][n]; }
;                 if (m & 1) asm volatile("" ::: "memory"); }
	v_pk_fma_f32 v[104:105], v[104:105], v[88:89], v[168:169]
	v_pk_fma_f32 v[102:103], v[102:103], v[86:87], v[166:167]
	global_store_dwordx4 v151, v[102:105], s[100:101] offset:512 nt
	global_load_dwordx4 v[166:169], v151, s[22:23] offset:512
	s_waitcnt vmcnt(15)
	v_pk_fma_f32 v[100:101], v[100:101], v[76:77], v[172:173]
	v_pk_fma_f32 v[98:99], v[98:99], v[74:75], v[170:171]
	global_store_dwordx4 v151, v[98:101], s[100:101] offset:576 nt
	global_load_dwordx4 v[170:173], v151, s[22:23] offset:576
	s_add_u32 s100, s70, 0x60000
	s_addc_u32 s101, s71, 0
	s_waitcnt vmcnt(15)
	v_pk_fma_f32 v[84:85], v[84:85], v[96:97], v[176:177]
	v_pk_fma_f32 v[82:83], v[82:83], v[94:95], v[174:175]
	global_store_dwordx4 v151, v[82:85], s[100:101] nt
	s_add_u32 s22, s70, 0x160000
	s_addc_u32 s23, s71, 0
	global_load_dwordx4 v[174:177], v151, s[22:23]
	s_waitcnt vmcnt(15)
	v_pk_fma_f32 v[80:81], v[80:81], v[92:93], v[184:185]
	v_pk_fma_f32 v[78:79], v[78:79], v[90:91], v[182:183]
	global_store_dwordx4 v151, v[78:81], s[100:101] offset:64 nt
	global_load_dwordx4 v[182:185], v151, s[22:23] offset:64
	s_waitcnt vmcnt(15)
	v_pk_fma_f32 v[72:73], v[72:73], v[88:89], v[188:189]
	v_pk_fma_f32 v[70:71], v[70:71], v[86:87], v[186:187]
	global_store_dwordx4 v151, v[70:73], s[100:101] offset:512 nt
	global_load_dwordx4 v[186:189], v151, s[22:23] offset:512
	s_waitcnt vmcnt(15)
	v_pk_fma_f32 v[68:69], v[68:69], v[76:77], v[192:193]
	v_pk_fma_f32 v[66:67], v[66:67], v[74:75], v[190:191]
	global_store_dwordx4 v151, v[66:69], s[100:101] offset:576 nt
	global_load_dwordx4 v[190:193], v151, s[22:23] offset:576
	s_add_u32 s100, s70, 0x100000
	s_addc_u32 s101, s71, 0
	s_waitcnt vmcnt(15)
	v_pk_fma_f32 v[64:65], v[64:65], v[96:97], v[220:221]
	v_pk_fma_f32 v[62:63], v[62:63], v[94:95], v[218:219]
	global_store_dwordx4 v151, v[62:65], s[100:101] nt
	s_waitcnt vmcnt(14)
	v_pk_fma_f32 v[60:61], v[60:61], v[92:93], v[224:225]
	v_pk_fma_f32 v[58:59], v[58:59], v[90:91], v[222:223]
	global_store_dwordx4 v151, v[58:61], s[100:101] offset:64 nt
	s_waitcnt vmcnt(13)
	v_pk_fma_f32 v[56:57], v[56:57], v[88:89], v[228:229]
	v_pk_fma_f32 v[54:55], v[54:55], v[86:87], v[226:227]
	global_store_dwordx4 v151, v[54:57], s[100:101] offset:512 nt
	s_waitcnt vmcnt(12)
	v_pk_fma_f32 v[52:53], v[52:53], v[76:77], v[232:233]
	v_pk_fma_f32 v[50:51], v[50:51], v[74:75], v[230:231]
	global_store_dwordx4 v151, v[50:53], s[100:101] offset:576 nt
	s_add_u32 s100, s70, 0x120000
	s_addc_u32 s101, s71, 0
	s_waitcnt vmcnt(11)
	v_pk_fma_f32 v[48:49], v[48:49], v[96:97], v[236:237]
	v_pk_fma_f32 v[46:47], v[46:47], v[94:95], v[234:235]
	global_store_dwordx4 v151, v[46:49], s[100:101] nt
	s_waitcnt vmcnt(10)
	v_pk_fma_f32 v[44:45], v[44:45], v[92:93], v[240:241]
	v_pk_fma_f32 v[42:43], v[42:43], v[90:91], v[238:239]
	global_store_dwordx4 v151, v[42:45], s[100:101] offset:64 nt
	s_waitcnt vmcnt(9)
	v_pk_fma_f32 v[40:41], v[40:41], v[88:89], v[244:245]
	v_pk_fma_f32 v[38:39], v[38:39], v[86:87], v[242:243]
	global_store_dwordx4 v151, v[38:41], s[100:101] offset:512 nt
	s_waitcnt vmcnt(8)
	v_pk_fma_f32 v[36:37], v[36:37], v[76:77], v[248:249]
	v_pk_fma_f32 v[34:35], v[34:35], v[74:75], v[246:247]
	global_store_dwordx4 v151, v[34:37], s[100:101] offset:576 nt
	s_add_u32 s100, s70, 0x140000
	s_addc_u32 s101, s71, 0
	s_waitcnt vmcnt(7)
	v_pk_fma_f32 v[32:33], v[32:33], v[96:97], v[160:161]
	v_pk_fma_f32 v[30:31], v[30:31], v[94:95], v[158:159]
	global_store_dwordx4 v151, v[30:33], s[100:101] nt
	s_waitcnt vmcnt(6)
	v_pk_fma_f32 v[28:29], v[28:29], v[92:93], v[164:165]
	v_pk_fma_f32 v[26:27], v[26:27], v[90:91], v[162:163]
	global_store_dwordx4 v151, v[26:29], s[100:101] offset:64 nt
	s_waitcnt vmcnt(5)
	v_pk_fma_f32 v[24:25], v[24:25], v[88:89], v[168:169]
	v_pk_fma_f32 v[22:23], v[22:23], v[86:87], v[166:167]
	global_store_dwordx4 v151, v[22:25], s[100:101] offset:512 nt
	s_waitcnt vmcnt(4)
	v_pk_fma_f32 v[20:21], v[20:21], v[76:77], v[172:173]
	v_pk_fma_f32 v[18:19], v[18:19], v[74:75], v[170:171]
	global_store_dwordx4 v151, v[18:21], s[100:101] offset:576 nt
	s_add_u32 s100, s70, 0x160000
	s_addc_u32 s101, s71, 0
	s_waitcnt vmcnt(3)
	v_pk_fma_f32 v[16:17], v[16:17], v[96:97], v[176:177]
	v_pk_fma_f32 v[14:15], v[14:15], v[94:95], v[174:175]
	global_store_dwordx4 v151, v[14:17], s[100:101] nt
	s_waitcnt vmcnt(2)
	v_pk_fma_f32 v[12:13], v[12:13], v[92:93], v[184:185]
	v_pk_fma_f32 v[10:11], v[10:11], v[90:91], v[182:183]
	global_store_dwordx4 v151, v[10:13], s[100:101] offset:64 nt
	s_waitcnt vmcnt(1)
	v_pk_fma_f32 v[8:9], v[8:9], v[88:89], v[188:189]
	v_pk_fma_f32 v[6:7], v[6:7], v[86:87], v[186:187]
	global_store_dwordx4 v151, v[6:9], s[100:101] offset:512 nt
	s_waitcnt vmcnt(0)
	v_pk_fma_f32 v[4:5], v[4:5], v[76:77], v[192:193]
	v_pk_fma_f32 v[2:3], v[2:3], v[74:75], v[190:191]
	global_store_dwordx4 v151, v[2:5], s[100:101] offset:576 nt
	s_mov_b64 s[22:23], -1
	s_andn2_b64 vcc, exec, s[14:15]
	s_waitcnt vmcnt(0)
	s_cbranch_vccnz .LBB0_1074
	s_andn2_b64 vcc, exec, s[0:1]
	s_cbranch_vccnz .LBB0_1073
	s_barrier
	s_branch .LBB0_1073
